# GU/in-proj K-loop: delete the now-redundant s_setprio 1 between the half-unit branch and the first MFMA (priority is already raised before the opening barrier)
# speedup vs baseline: 1.0042x; 1.0042x over previous
; #define PG8_STAGE(bufoff, gbase, voff) do { _Pragma("unroll") for (int _i = 0; _i < 2; ++_i) \
;         __builtin_amdgcn_global_load_lds((const unsigned*)((const char*)(gbase) + (voff)[_i]), (PG8_LAS unsigned*)(lds + (bufoff) + ldsw + _i * 8192), 16, 0, 0); } while (0)
; #define PG8_LDA(dst, b, h) do { _Pragma("unroll") for (int m = 0; m < 4; ++m) _Pragma("unroll") for (int k = 0; k < 2; ++k) dst[m][k] = *(const PG8_LAS bf16x8*)(lds + PG8_SA(b, h) + aoff + m * 2048 + k * 1024); } while (0)
; #define PG8_LDB(dst, b, h) do { _Pragma("unroll") for (int n = 0; n < 2; ++n) _Pragma("unroll") for (int k = 0; k < 2; ++k) dst[n][k] = *(const PG8_LAS bf16x8*)(lds + PG8_SB(b, h) + boff + n * 2048 + k * 1024); } while (0)
; #define PG8_MMA(ai, bj, At, Bt) do { __builtin_amdgcn_s_setprio(1); _Pragma("unroll") for (int m = 0; m < 4; ++m) _Pragma("unroll") for (int n = 0; n < 2; ++n) _Pragma("unroll") for (int k = 0; k < 2; ++k) \
;         acc[ai][bj][m][n] = __builtin_amdgcn_mfma_f32_16x16x32_bf16(Bt[n][k], At[m][k], acc[ai][bj][m][n], 0, 0, 0); __builtin_amdgcn_s_setprio(0); } while (0)
; #define PG8_WAIT_V(n) asm volatile("s_waitcnt vmcnt(" #n ")" ::: "memory")
; #define PG8_WAIT_L(n) asm volatile("s_waitcnt lgkmcnt(" #n ")" ::: "memory")
; #define PG8_BAR __builtin_amdgcn_s_barrier()
; #define PG8_SCHED __builtin_amdgcn_sched_barrier(0)
; template <class Epi, class Sched, bool ALIGN_EPI = false, bool SP2 = false>
; __device__ __forceinline__ void gemm_phase(PG8_LAS unsigned char* lds, const Gemm g, const Sched& S, const Epi& E) {
;     ...
;             PG8_LDB(B0, 0, 0); PG8_LDB(B1, 0, 1); PG8_SCHED; PG8_LDA(At, 0, 0); PG8_STAGE(PG8_SA(1, 1), a1 + hstep, voffA);
;             PG8_WAIT_V(8); PG8_WAIT_L(0); PG8_BAR; PG8_MMA(0, 0, At, B0); PG8_MMA(0, 1, At, B1); PG8_BAR; PG8_SCHED;
;             if (full) PG8_LDA(At, 0, 1); PG8_STAGE(PG8_SB(0, 0), b2, voffB); PG8_STAGE(PG8_SB(0, 1), b2 + hstep, voffB); PG8_STAGE(PG8_SA(0, 0), a2, voffA);
;             PG8_WAIT_V(8); PG8_WAIT_L(0); PG8_BAR; if (full) { PG8_MMA(1, 0, At, B0); PG8_MMA(1, 1, At, B1); } PG8_BAR; PG8_SCHED;
.LBB0_294:
	s_add_u32 s38, s36, 0xfffc0080
	s_addc_u32 s39, s37, -1
	s_cmp_eq_u32 s89, 12
	s_cselect_b32 s43, s23, s39
	s_cselect_b32 s42, s81, s38
	s_cselect_b32 s39, s21, s88
	s_cselect_b32 s38, s82, s83
	s_mov_b32 m0, s54
	v_lshl_add_u64 v[2:3], s[38:39], 0, v[198:199]
	s_add_u32 s90, s38, 0x40000
	global_load_lds_dwordx4 v[2:3], off
	v_lshl_add_u64 v[208:209], s[38:39], 0, v[202:203]
	s_mov_b32 m0, s55
	s_addc_u32 s91, s39, 0
	global_load_lds_dwordx4 v[208:209], off
	v_lshl_add_u64 v[210:211], s[90:91], 0, v[198:199]
	s_mov_b32 m0, s56
	v_lshl_add_u64 v[220:221], s[42:43], 0, v[200:201]
	global_load_lds_dwordx4 v[210:211], off
	v_lshl_add_u64 v[210:211], s[90:91], 0, v[202:203]
	s_mov_b32 m0, s57
	s_and_b64 vcc, exec, s[4:5]
	global_load_lds_dwordx4 v[210:211], off
	v_lshl_add_u64 v[210:211], s[42:43], 0, v[196:197]
	s_mov_b32 m0, s31
	s_nop 0
	global_load_lds_dwordx4 v[210:211], off
	s_mov_b32 m0, s58
	s_nop 0
	global_load_lds_dwordx4 v[220:221], off
	s_waitcnt vmcnt(8)
	s_waitcnt lgkmcnt(0)
	s_setprio 1
	s_barrier
	s_cbranch_vccnz .LBB0_296
	v_mfma_f32_16x16x32_bf16 v[64:67], v[148:151], v[176:179], v[64:67]
	v_mfma_f32_16x16x32_bf16 v[56:59], v[156:159], v[176:179], v[56:59]
	v_mfma_f32_16x16x32_bf16 v[48:51], v[148:151], v[172:175], v[48:51]
	v_mfma_f32_16x16x32_bf16 v[40:43], v[156:159], v[172:175], v[40:43]
	v_mfma_f32_16x16x32_bf16 v[32:35], v[148:151], v[168:171], v[32:35]
	v_mfma_f32_16x16x32_bf16 v[24:27], v[156:159], v[168:171], v[24:27]
	v_mfma_f32_16x16x32_bf16 v[16:19], v[148:151], v[164:167], v[16:19]
	v_mfma_f32_16x16x32_bf16 v[8:11], v[156:159], v[164:167], v[8:11]
	v_mfma_f32_16x16x32_bf16 v[64:67], v[152:155], v[192:195], v[64:67]
	v_mfma_f32_16x16x32_bf16 v[56:59], v[160:163], v[192:195], v[56:59]
	v_mfma_f32_16x16x32_bf16 v[48:51], v[152:155], v[188:191], v[48:51]
	v_mfma_f32_16x16x32_bf16 v[40:43], v[160:163], v[188:191], v[40:43]
	v_mfma_f32_16x16x32_bf16 v[32:35], v[152:155], v[184:187], v[32:35]
	v_mfma_f32_16x16x32_bf16 v[24:27], v[160:163], v[184:187], v[24:27]
	v_mfma_f32_16x16x32_bf16 v[16:19], v[152:155], v[180:183], v[16:19]
	v_mfma_f32_16x16x32_bf16 v[8:11], v[160:163], v[180:183], v[8:11]
	v_mfma_f32_16x16x32_bf16 v[60:63], v[132:135], v[176:179], v[60:63]
	v_mfma_f32_16x16x32_bf16 v[52:55], v[140:143], v[176:179], v[52:55]
	v_mfma_f32_16x16x32_bf16 v[44:47], v[132:135], v[172:175], v[44:47]
	v_mfma_f32_16x16x32_bf16 v[36:39], v[140:143], v[172:175], v[36:39]
	v_mfma_f32_16x16x32_bf16 v[28:31], v[132:135], v[168:171], v[28:31]
	v_mfma_f32_16x16x32_bf16 v[20:23], v[140:143], v[168:171], v[20:23]
	v_mfma_f32_16x16x32_bf16 v[12:15], v[132:135], v[164:167], v[12:15]
	v_mfma_f32_16x16x32_bf16 v[4:7], v[140:143], v[164:167], v[4:7]
	v_mfma_f32_16x16x32_bf16 v[60:63], v[136:139], v[192:195], v[60:63]
	v_mfma_f32_16x16x32_bf16 v[52:55], v[144:147], v[192:195], v[52:55]
	v_mfma_f32_16x16x32_bf16 v[44:47], v[136:139], v[188:191], v[44:47]
	v_mfma_f32_16x16x32_bf16 v[36:39], v[144:147], v[188:191], v[36:39]
	v_mfma_f32_16x16x32_bf16 v[28:31], v[136:139], v[184:187], v[28:31]
	v_mfma_f32_16x16x32_bf16 v[20:23], v[144:147], v[184:187], v[20:23]
	v_mfma_f32_16x16x32_bf16 v[12:15], v[136:139], v[180:183], v[12:15]
	v_mfma_f32_16x16x32_bf16 v[4:7], v[144:147], v[180:183], v[4:7]

; #define PG8_STAGE(bufoff, gbase, voff) do { _Pragma("unroll") for (int _i = 0; _i < 2; ++_i) \
;         __builtin_amdgcn_global_load_lds((const unsigned*)((const char*)(gbase) + (voff)[_i]), (PG8_LAS unsigned*)(lds + (bufoff) + ldsw + _i * 8192), 16, 0, 0); } while (0)
; #define PG8_LDA(dst, b, h) do { _Pragma("unroll") for (int m = 0; m < 4; ++m) _Pragma("unroll") for (int k = 0; k < 2; ++k) dst[m][k] = *(const PG8_LAS bf16x8*)(lds + PG8_SA(b, h) + aoff + m * 2048 + k * 1024); } while (0)
; #define PG8_LDB(dst, b, h) do { _Pragma("unroll") for (int n = 0; n < 2; ++n) _Pragma("unroll") for (int k = 0; k < 2; ++k) dst[n][k] = *(const PG8_LAS bf16x8*)(lds + PG8_SB(b, h) + boff + n * 2048 + k * 1024); } while (0)
; #define PG8_MMA(ai, bj, At, Bt) do { __builtin_amdgcn_s_setprio(1); _Pragma("unroll") for (int m = 0; m < 4; ++m) _Pragma("unroll") for (int n = 0; n < 2; ++n) _Pragma("unroll") for (int k = 0; k < 2; ++k) \
;         acc[ai][bj][m][n] = __builtin_amdgcn_mfma_f32_16x16x32_bf16(Bt[n][k], At[m][k], acc[ai][bj][m][n], 0, 0, 0); __builtin_amdgcn_s_setprio(0); } while (0)
; #define PG8_WAIT_V(n) asm volatile("s_waitcnt vmcnt(" #n ")" ::: "memory")
; #define PG8_WAIT_L(n) asm volatile("s_waitcnt lgkmcnt(" #n ")" ::: "memory")
; #define PG8_BAR __builtin_amdgcn_s_barrier()
; #define PG8_SCHED __builtin_amdgcn_sched_barrier(0)
; template <class Epi, class Sched, bool ALIGN_EPI = false, bool SP2 = false>
; __device__ __forceinline__ void gemm_phase(PG8_LAS unsigned char* lds, const Gemm g, const Sched& S, const Epi& E) {
;     ...
;             PG8_LDB(B0, 1, 0); PG8_LDB(B1, 1, 1); PG8_SCHED; PG8_LDA(At, 1, 0); PG8_STAGE(PG8_SA(0, 1), a2 + hstep, voffA);
;             PG8_WAIT_V(8); PG8_WAIT_L(0); PG8_BAR; PG8_MMA(0, 0, At, B0); PG8_MMA(0, 1, At, B1); PG8_BAR; PG8_SCHED;
;             if (full) PG8_LDA(At, 1, 1); PG8_STAGE(PG8_SB(1, 0), b3, voffB); PG8_STAGE(PG8_SB(1, 1), b3 + hstep, voffB); PG8_STAGE(PG8_SA(1, 0), a3, voffA);
;             PG8_WAIT_V(8); PG8_WAIT_L(0); PG8_BAR; if (full) { PG8_MMA(1, 0, At, B0); PG8_MMA(1, 1, At, B1); } PG8_BAR; PG8_SCHED;
.LBB0_298:
	s_mov_b32 m0, s61
	v_lshl_add_u64 v[2:3], v[2:3], 0, s[52:53]
	s_add_u32 s38, s38, 0x40080
	global_load_lds_dwordx4 v[2:3], off
	v_lshl_add_u64 v[2:3], v[208:209], 0, s[52:53]
	s_mov_b32 m0, s62
	s_addc_u32 s39, s39, 0
	global_load_lds_dwordx4 v[2:3], off
	v_lshl_add_u64 v[2:3], s[38:39], 0, v[198:199]
	s_mov_b32 m0, s65
	s_and_b64 vcc, exec, s[4:5]
	global_load_lds_dwordx4 v[2:3], off
	v_lshl_add_u64 v[2:3], s[38:39], 0, v[202:203]
	s_mov_b32 m0, s68
	s_nop 0
	global_load_lds_dwordx4 v[2:3], off
	v_lshl_add_u64 v[2:3], v[210:211], 0, s[52:53]
	s_mov_b32 m0, s63
	s_nop 0
	global_load_lds_dwordx4 v[2:3], off
	v_lshl_add_u64 v[2:3], v[220:221], 0, s[52:53]
	s_mov_b32 m0, s64
	s_nop 0
	global_load_lds_dwordx4 v[2:3], off
	s_waitcnt vmcnt(8)
	s_waitcnt lgkmcnt(0)
	s_setprio 1
	s_barrier
	s_cbranch_vccnz .LBB0_291
	v_mfma_f32_16x16x32_bf16 v[64:67], v[148:151], v[176:179], v[64:67]
	v_mfma_f32_16x16x32_bf16 v[56:59], v[156:159], v[176:179], v[56:59]
	v_mfma_f32_16x16x32_bf16 v[48:51], v[148:151], v[172:175], v[48:51]
	v_mfma_f32_16x16x32_bf16 v[40:43], v[156:159], v[172:175], v[40:43]
	v_mfma_f32_16x16x32_bf16 v[32:35], v[148:151], v[168:171], v[32:35]
	v_mfma_f32_16x16x32_bf16 v[24:27], v[156:159], v[168:171], v[24:27]
	v_mfma_f32_16x16x32_bf16 v[16:19], v[148:151], v[164:167], v[16:19]
	v_mfma_f32_16x16x32_bf16 v[8:11], v[156:159], v[164:167], v[8:11]
	v_mfma_f32_16x16x32_bf16 v[64:67], v[152:155], v[192:195], v[64:67]
	v_mfma_f32_16x16x32_bf16 v[56:59], v[160:163], v[192:195], v[56:59]
	v_mfma_f32_16x16x32_bf16 v[48:51], v[152:155], v[188:191], v[48:51]
	v_mfma_f32_16x16x32_bf16 v[40:43], v[160:163], v[188:191], v[40:43]
	v_mfma_f32_16x16x32_bf16 v[32:35], v[152:155], v[184:187], v[32:35]
	v_mfma_f32_16x16x32_bf16 v[24:27], v[160:163], v[184:187], v[24:27]
	v_mfma_f32_16x16x32_bf16 v[16:19], v[152:155], v[180:183], v[16:19]
	v_mfma_f32_16x16x32_bf16 v[8:11], v[160:163], v[180:183], v[8:11]
	v_mfma_f32_16x16x32_bf16 v[60:63], v[132:135], v[176:179], v[60:63]
	v_mfma_f32_16x16x32_bf16 v[52:55], v[140:143], v[176:179], v[52:55]
	v_mfma_f32_16x16x32_bf16 v[44:47], v[132:135], v[172:175], v[44:47]
	v_mfma_f32_16x16x32_bf16 v[36:39], v[140:143], v[172:175], v[36:39]
	v_mfma_f32_16x16x32_bf16 v[28:31], v[132:135], v[168:171], v[28:31]
	v_mfma_f32_16x16x32_bf16 v[20:23], v[140:143], v[168:171], v[20:23]
	v_mfma_f32_16x16x32_bf16 v[12:15], v[132:135], v[164:167], v[12:15]
	v_mfma_f32_16x16x32_bf16 v[2:5], v[140:143], v[164:167], v[4:7]
	v_mfma_f32_16x16x32_bf16 v[60:63], v[136:139], v[192:195], v[60:63]
	v_mfma_f32_16x16x32_bf16 v[52:55], v[144:147], v[192:195], v[52:55]
	v_mfma_f32_16x16x32_bf16 v[44:47], v[136:139], v[188:191], v[44:47]
	v_mfma_f32_16x16x32_bf16 v[36:39], v[144:147], v[188:191], v[36:39]
	v_mfma_f32_16x16x32_bf16 v[28:31], v[136:139], v[184:187], v[28:31]
	v_mfma_f32_16x16x32_bf16 v[20:23], v[144:147], v[184:187], v[20:23]
	v_mfma_f32_16x16x32_bf16 v[12:15], v[136:139], v[180:183], v[12:15]
	v_mfma_f32_16x16x32_bf16 v[4:7], v[144:147], v[180:183], v[2:5]
	s_branch .LBB0_291

; #define PG8_STAGE(bufoff, gbase, voff) do { _Pragma("unroll") for (int _i = 0; _i < 2; ++_i) \
;         __builtin_amdgcn_global_load_lds((const unsigned*)((const char*)(gbase) + (voff)[_i]), (PG8_LAS unsigned*)(lds + (bufoff) + ldsw + _i * 8192), 16, 0, 0); } while (0)
; #define PG8_LDA(dst, b, h) do { _Pragma("unroll") for (int m = 0; m < 4; ++m) _Pragma("unroll") for (int k = 0; k < 2; ++k) dst[m][k] = *(const PG8_LAS bf16x8*)(lds + PG8_SA(b, h) + aoff + m * 2048 + k * 1024); } while (0)
; #define PG8_LDB(dst, b, h) do { _Pragma("unroll") for (int n = 0; n < 2; ++n) _Pragma("unroll") for (int k = 0; k < 2; ++k) dst[n][k] = *(const PG8_LAS bf16x8*)(lds + PG8_SB(b, h) + boff + n * 2048 + k * 1024); } while (0)
; #define PG8_MMA(ai, bj, At, Bt) do { __builtin_amdgcn_s_setprio(1); _Pragma("unroll") for (int m = 0; m < 4; ++m) _Pragma("unroll") for (int n = 0; n < 2; ++n) _Pragma("unroll") for (int k = 0; k < 2; ++k) \
;         acc[ai][bj][m][n] = __builtin_amdgcn_mfma_f32_16x16x32_bf16(Bt[n][k], At[m][k], acc[ai][bj][m][n], 0, 0, 0); __builtin_amdgcn_s_setprio(0); } while (0)
; #define PG8_WAIT_V(n) asm volatile("s_waitcnt vmcnt(" #n ")" ::: "memory")
; #define PG8_WAIT_L(n) asm volatile("s_waitcnt lgkmcnt(" #n ")" ::: "memory")
; #define PG8_BAR __builtin_amdgcn_s_barrier()
; #define PG8_SCHED __builtin_amdgcn_sched_barrier(0)
; template <class Epi, class Sched, bool ALIGN_EPI = false, bool SP2 = false>
; __device__ __forceinline__ void gemm_phase(PG8_LAS unsigned char* lds, const Gemm g, const Sched& S, const Epi& E) {
;     ...
;             PG8_LDB(B0, 0, 0); PG8_LDB(B1, 0, 1); PG8_SCHED; PG8_LDA(At, 0, 0); PG8_STAGE(PG8_SA(1, 1), a1 + hstep, voffA);
;             PG8_WAIT_V(8); PG8_WAIT_L(0); PG8_BAR; PG8_MMA(0, 0, At, B0); PG8_MMA(0, 1, At, B1); PG8_BAR; PG8_SCHED;
;             if (full) PG8_LDA(At, 0, 1); PG8_STAGE(PG8_SB(0, 0), b2, voffB); PG8_STAGE(PG8_SB(0, 1), b2 + hstep, voffB); PG8_STAGE(PG8_SA(0, 0), a2, voffA);
;             PG8_WAIT_V(8); PG8_WAIT_L(0); PG8_BAR; if (full) { PG8_MMA(1, 0, At, B0); PG8_MMA(1, 1, At, B1); } PG8_BAR; PG8_SCHED;
.LBB0_523:
	s_add_u32 s36, s34, 0xfffc0080
	s_addc_u32 s37, s35, -1
	s_cmp_eq_u32 s82, 12
	s_cselect_b32 s39, s1, s37
	s_cselect_b32 s38, s19, s36
	s_cselect_b32 s37, s17, s81
	s_cselect_b32 s36, s29, s80
	s_mov_b32 m0, s49
	v_lshl_add_u64 v[2:3], s[36:37], 0, v[198:199]
	s_add_u32 s88, s36, 0x40000
	global_load_lds_dwordx4 v[2:3], off
	v_lshl_add_u64 v[208:209], s[36:37], 0, v[202:203]
	s_mov_b32 m0, s54
	s_addc_u32 s89, s37, 0
	global_load_lds_dwordx4 v[208:209], off
	v_lshl_add_u64 v[210:211], s[88:89], 0, v[198:199]
	s_mov_b32 m0, s55
	v_lshl_add_u64 v[220:221], s[38:39], 0, v[200:201]
	global_load_lds_dwordx4 v[210:211], off
	v_lshl_add_u64 v[210:211], s[88:89], 0, v[202:203]
	s_mov_b32 m0, s56
	s_and_b64 vcc, exec, s[4:5]
	global_load_lds_dwordx4 v[210:211], off
	v_lshl_add_u64 v[210:211], s[38:39], 0, v[196:197]
	s_mov_b32 m0, s27
	s_nop 0
	global_load_lds_dwordx4 v[210:211], off
	s_mov_b32 m0, s57
	s_nop 0
	global_load_lds_dwordx4 v[220:221], off
	s_waitcnt vmcnt(8)
	s_waitcnt lgkmcnt(0)
	s_setprio 1
	s_barrier
	s_cbranch_vccnz .LBB0_525
	v_mfma_f32_16x16x32_bf16 v[64:67], v[148:151], v[176:179], v[64:67]
	v_mfma_f32_16x16x32_bf16 v[60:63], v[156:159], v[176:179], v[60:63]
	v_mfma_f32_16x16x32_bf16 v[48:51], v[148:151], v[172:175], v[48:51]
	v_mfma_f32_16x16x32_bf16 v[44:47], v[156:159], v[172:175], v[44:47]
	v_mfma_f32_16x16x32_bf16 v[32:35], v[148:151], v[168:171], v[32:35]
	v_mfma_f32_16x16x32_bf16 v[28:31], v[156:159], v[168:171], v[28:31]
	v_mfma_f32_16x16x32_bf16 v[16:19], v[148:151], v[164:167], v[16:19]
	v_mfma_f32_16x16x32_bf16 v[12:15], v[156:159], v[164:167], v[12:15]
	v_mfma_f32_16x16x32_bf16 v[64:67], v[152:155], v[192:195], v[64:67]
	v_mfma_f32_16x16x32_bf16 v[60:63], v[160:163], v[192:195], v[60:63]
	v_mfma_f32_16x16x32_bf16 v[48:51], v[152:155], v[188:191], v[48:51]
	v_mfma_f32_16x16x32_bf16 v[44:47], v[160:163], v[188:191], v[44:47]
	v_mfma_f32_16x16x32_bf16 v[32:35], v[152:155], v[184:187], v[32:35]
	v_mfma_f32_16x16x32_bf16 v[28:31], v[160:163], v[184:187], v[28:31]
	v_mfma_f32_16x16x32_bf16 v[16:19], v[152:155], v[180:183], v[16:19]
	v_mfma_f32_16x16x32_bf16 v[12:15], v[160:163], v[180:183], v[12:15]
	v_mfma_f32_16x16x32_bf16 v[56:59], v[132:135], v[176:179], v[56:59]
	v_mfma_f32_16x16x32_bf16 v[52:55], v[140:143], v[176:179], v[52:55]
	v_mfma_f32_16x16x32_bf16 v[40:43], v[132:135], v[172:175], v[40:43]
	v_mfma_f32_16x16x32_bf16 v[36:39], v[140:143], v[172:175], v[36:39]
	v_mfma_f32_16x16x32_bf16 v[24:27], v[132:135], v[168:171], v[24:27]
	v_mfma_f32_16x16x32_bf16 v[20:23], v[140:143], v[168:171], v[20:23]
	v_mfma_f32_16x16x32_bf16 v[8:11], v[132:135], v[164:167], v[8:11]
	v_mfma_f32_16x16x32_bf16 v[4:7], v[140:143], v[164:167], v[4:7]
	v_mfma_f32_16x16x32_bf16 v[56:59], v[136:139], v[192:195], v[56:59]
	v_mfma_f32_16x16x32_bf16 v[52:55], v[144:147], v[192:195], v[52:55]
	v_mfma_f32_16x16x32_bf16 v[40:43], v[136:139], v[188:191], v[40:43]
	v_mfma_f32_16x16x32_bf16 v[36:39], v[144:147], v[188:191], v[36:39]
	v_mfma_f32_16x16x32_bf16 v[24:27], v[136:139], v[184:187], v[24:27]
	v_mfma_f32_16x16x32_bf16 v[20:23], v[144:147], v[184:187], v[20:23]
	v_mfma_f32_16x16x32_bf16 v[8:11], v[136:139], v[180:183], v[8:11]
	v_mfma_f32_16x16x32_bf16 v[4:7], v[144:147], v[180:183], v[4:7]

; #define PG8_STAGE(bufoff, gbase, voff) do { _Pragma("unroll") for (int _i = 0; _i < 2; ++_i) \
;         __builtin_amdgcn_global_load_lds((const unsigned*)((const char*)(gbase) + (voff)[_i]), (PG8_LAS unsigned*)(lds + (bufoff) + ldsw + _i * 8192), 16, 0, 0); } while (0)
; #define PG8_LDA(dst, b, h) do { _Pragma("unroll") for (int m = 0; m < 4; ++m) _Pragma("unroll") for (int k = 0; k < 2; ++k) dst[m][k] = *(const PG8_LAS bf16x8*)(lds + PG8_SA(b, h) + aoff + m * 2048 + k * 1024); } while (0)
; #define PG8_LDB(dst, b, h) do { _Pragma("unroll") for (int n = 0; n < 2; ++n) _Pragma("unroll") for (int k = 0; k < 2; ++k) dst[n][k] = *(const PG8_LAS bf16x8*)(lds + PG8_SB(b, h) + boff + n * 2048 + k * 1024); } while (0)
; #define PG8_MMA(ai, bj, At, Bt) do { __builtin_amdgcn_s_setprio(1); _Pragma("unroll") for (int m = 0; m < 4; ++m) _Pragma("unroll") for (int n = 0; n < 2; ++n) _Pragma("unroll") for (int k = 0; k < 2; ++k) \
;         acc[ai][bj][m][n] = __builtin_amdgcn_mfma_f32_16x16x32_bf16(Bt[n][k], At[m][k], acc[ai][bj][m][n], 0, 0, 0); __builtin_amdgcn_s_setprio(0); } while (0)
; #define PG8_WAIT_V(n) asm volatile("s_waitcnt vmcnt(" #n ")" ::: "memory")
; #define PG8_WAIT_L(n) asm volatile("s_waitcnt lgkmcnt(" #n ")" ::: "memory")
; #define PG8_BAR __builtin_amdgcn_s_barrier()
; #define PG8_SCHED __builtin_amdgcn_sched_barrier(0)
; template <class Epi, class Sched, bool ALIGN_EPI = false, bool SP2 = false>
; __device__ __forceinline__ void gemm_phase(PG8_LAS unsigned char* lds, const Gemm g, const Sched& S, const Epi& E) {
;     ...
;             PG8_LDB(B0, 1, 0); PG8_LDB(B1, 1, 1); PG8_SCHED; PG8_LDA(At, 1, 0); PG8_STAGE(PG8_SA(0, 1), a2 + hstep, voffA);
;             PG8_WAIT_V(8); PG8_WAIT_L(0); PG8_BAR; PG8_MMA(0, 0, At, B0); PG8_MMA(0, 1, At, B1); PG8_BAR; PG8_SCHED;
;             if (full) PG8_LDA(At, 1, 1); PG8_STAGE(PG8_SB(1, 0), b3, voffB); PG8_STAGE(PG8_SB(1, 1), b3 + hstep, voffB); PG8_STAGE(PG8_SA(1, 0), a3, voffA);
;             PG8_WAIT_V(8); PG8_WAIT_L(0); PG8_BAR; if (full) { PG8_MMA(1, 0, At, B0); PG8_MMA(1, 1, At, B1); } PG8_BAR; PG8_SCHED;
.LBB0_527:
	s_mov_b32 m0, s62
	v_lshl_add_u64 v[2:3], v[2:3], 0, s[52:53]
	s_add_u32 s36, s36, 0x40080
	global_load_lds_dwordx4 v[2:3], off
	v_lshl_add_u64 v[2:3], v[208:209], 0, s[52:53]
	s_mov_b32 m0, s63
	s_addc_u32 s37, s37, 0
	global_load_lds_dwordx4 v[2:3], off
	v_lshl_add_u64 v[2:3], s[36:37], 0, v[198:199]
	s_mov_b32 m0, s68
	s_and_b64 vcc, exec, s[4:5]
	global_load_lds_dwordx4 v[2:3], off
	v_lshl_add_u64 v[2:3], s[36:37], 0, v[202:203]
	s_mov_b32 m0, s69
	s_nop 0
	global_load_lds_dwordx4 v[2:3], off
	v_lshl_add_u64 v[2:3], v[210:211], 0, s[52:53]
	s_mov_b32 m0, s64
	s_nop 0
	global_load_lds_dwordx4 v[2:3], off
	v_lshl_add_u64 v[2:3], v[220:221], 0, s[52:53]
	s_mov_b32 m0, s65
	s_nop 0
	global_load_lds_dwordx4 v[2:3], off
	s_waitcnt vmcnt(8)
	s_waitcnt lgkmcnt(0)
	s_setprio 1
	s_barrier
	s_cbranch_vccnz .LBB0_520
	v_mfma_f32_16x16x32_bf16 v[64:67], v[148:151], v[176:179], v[64:67]
	v_mfma_f32_16x16x32_bf16 v[60:63], v[156:159], v[176:179], v[60:63]
	v_mfma_f32_16x16x32_bf16 v[48:51], v[148:151], v[172:175], v[48:51]
	v_mfma_f32_16x16x32_bf16 v[44:47], v[156:159], v[172:175], v[44:47]
	v_mfma_f32_16x16x32_bf16 v[32:35], v[148:151], v[168:171], v[32:35]
	v_mfma_f32_16x16x32_bf16 v[28:31], v[156:159], v[168:171], v[28:31]
	v_mfma_f32_16x16x32_bf16 v[16:19], v[148:151], v[164:167], v[16:19]
	v_mfma_f32_16x16x32_bf16 v[12:15], v[156:159], v[164:167], v[12:15]
	v_mfma_f32_16x16x32_bf16 v[64:67], v[152:155], v[192:195], v[64:67]
	v_mfma_f32_16x16x32_bf16 v[60:63], v[160:163], v[192:195], v[60:63]
	v_mfma_f32_16x16x32_bf16 v[48:51], v[152:155], v[188:191], v[48:51]
	v_mfma_f32_16x16x32_bf16 v[44:47], v[160:163], v[188:191], v[44:47]
	v_mfma_f32_16x16x32_bf16 v[32:35], v[152:155], v[184:187], v[32:35]
	v_mfma_f32_16x16x32_bf16 v[28:31], v[160:163], v[184:187], v[28:31]
	v_mfma_f32_16x16x32_bf16 v[16:19], v[152:155], v[180:183], v[16:19]
	v_mfma_f32_16x16x32_bf16 v[12:15], v[160:163], v[180:183], v[12:15]
	v_mfma_f32_16x16x32_bf16 v[56:59], v[132:135], v[176:179], v[56:59]
	v_mfma_f32_16x16x32_bf16 v[52:55], v[140:143], v[176:179], v[52:55]
	v_mfma_f32_16x16x32_bf16 v[40:43], v[132:135], v[172:175], v[40:43]
	v_mfma_f32_16x16x32_bf16 v[36:39], v[140:143], v[172:175], v[36:39]
	v_mfma_f32_16x16x32_bf16 v[24:27], v[132:135], v[168:171], v[24:27]
	v_mfma_f32_16x16x32_bf16 v[20:23], v[140:143], v[168:171], v[20:23]
	v_mfma_f32_16x16x32_bf16 v[8:11], v[132:135], v[164:167], v[8:11]
	v_mfma_f32_16x16x32_bf16 v[2:5], v[140:143], v[164:167], v[4:7]
	v_mfma_f32_16x16x32_bf16 v[56:59], v[136:139], v[192:195], v[56:59]
	v_mfma_f32_16x16x32_bf16 v[52:55], v[144:147], v[192:195], v[52:55]
	v_mfma_f32_16x16x32_bf16 v[40:43], v[136:139], v[188:191], v[40:43]
	v_mfma_f32_16x16x32_bf16 v[36:39], v[144:147], v[188:191], v[36:39]
	v_mfma_f32_16x16x32_bf16 v[24:27], v[136:139], v[184:187], v[24:27]
	v_mfma_f32_16x16x32_bf16 v[20:23], v[144:147], v[184:187], v[20:23]
	v_mfma_f32_16x16x32_bf16 v[8:11], v[136:139], v[180:183], v[8:11]
	v_mfma_f32_16x16x32_bf16 v[4:7], v[144:147], v[180:183], v[2:5]
	s_branch .LBB0_520
